# MoBA: next-tile LDS-DMA issue moved to after the QK MFMAs (fills the MFMA-to-VALU dependency gap) instead of before them
# speedup vs baseline: 1.0026x; 1.0026x over previous
; __device__ void moba_item(const P& p, int bh, int qt, char* smem) {
;     ...
;     if (tt + 2 < ntiles) {
;       const int k1 = (tt + 2) * 64;
; #pragma unroll
;       for (int i = 0; i < 4; ++i) {
;         rk[i] = *(const u32x4*)(Kp + (size_t)(k1 + kr + 16 * i) * 128 + kc * 8);
;         rv[i] = *(const u32x4*)(VT + (size_t)(vr + 32 * i) * 4096 + k1 + vc * 8);
;       }
;     }
;     const int blk = tt >> 2;
;     const bool own = (blk == qblk);
;     const bool rowvalid = own || ((mymask >> blk) & 1u);
;     if (__any(rowvalid)) {
;       const int key0 = tt * 64;
;       f32x4 sacc[2][2];
; #pragma unroll
;       for (int st = 0; st < 2; ++st)
; #pragma unroll
;         for (int kt = 0; kt < 2; ++kt) {
;           sacc[st][kt] = (f32x4){0.f, 0.f, 0.f, 0.f};
;           const int row = 32 * st + 8 * (li >> 2) + 4 * kt + (li & 3);
; #pragma unroll
;           for (int kk = 0; kk < 4; ++kk) {
;             const bf16x8 kf = *(const bf16x8*)(sK + row * 256 + (((kk * 4 + g) ^ li) << 4));
;             sacc[st][kt] = __builtin_amdgcn_mfma_f32_16x16x32_bf16(kf, qf[kk], sacc[st][kt], 0, 0, 0);
;           }
;         }
;       const bool diag = (tt == ntiles - 1);
;       float mx = -INFINITY;
;       if (diag || !__all(rowvalid)) {
; #pragma unroll
;         for (int st = 0; st < 2; ++st)
; #pragma unroll
;           for (int kt = 0; kt < 2; ++kt)
; #pragma unroll
;             for (int r = 0; r < 4; ++r) {
;               const int key = key0 + 32 * st + 8 * g + 4 * kt + r;
;               bool ok = rowvalid && (!diag || key <= qpos);
;               const float sv = ok ? sacc[st][kt][r] * SC : -INFINITY;
;               sacc[st][kt][r] = sv;
;               mx = fmaxf(mx, sv);
;             }
;       } else {
; #pragma unroll
;         for (int st = 0; st < 2; ++st)
; #pragma unroll
;           for (int kt = 0; kt < 2; ++kt) {
;             sacc[st][kt] *= SC;
;             mx = fmaxf(mx, fmaxf(fmaxf(sacc[st][kt][0], sacc[st][kt][1]), fmaxf(sacc[st][kt][2], sacc[st][kt][3])));
;           }
;       }
.LBB0_616:
	s_lshr_b32 s6, s27, 2
	s_cmp_eq_u32 s6, s41
	s_cselect_b64 s[0:1], -1, 0
	s_lshl_b32 s6, 1, s6
	v_and_b32_e32 v0, s6, v149
	v_cmp_ne_u32_e32 vcc, 0, v0
	s_or_b64 s[6:7], s[0:1], vcc
	s_mov_b64 vcc, s[6:7]
	s_cbranch_vccz .LBB0_625
	v_add_u32_e32 v0, v155, v151
	v_add_u32_e32 v2, v155, v178
	v_add_u32_e32 v3, v155, v179
	v_add_u32_e32 v168, v155, v180
	s_cmp_eq_u32 s40, s27
	s_cselect_b64 s[0:1], -1, 0
	s_and_b64 vcc, exec, s[0:1]
	s_mov_b64 s[10:11], s[0:1]
	ds_read_b128 v[194:197], v0
	ds_read_b128 v[198:201], v0 offset:1024
	ds_read_b128 v[202:205], v0 offset:8192
	ds_read_b128 v[220:223], v0 offset:9216
	ds_read_b128 v[224:227], v2
	ds_read_b128 v[228:231], v2 offset:1024
	ds_read_b128 v[232:235], v2 offset:8192
	ds_read_b128 v[4:7], v2 offset:9216
	ds_read_b128 v[8:11], v3
	ds_read_b128 v[12:15], v3 offset:1024
	ds_read_b128 v[16:19], v3 offset:8192
	ds_read_b128 v[164:167], v3 offset:9216
	s_waitcnt lgkmcnt(8)
	v_mfma_f32_16x16x32_bf16 v[132:135], v[194:197], v[20:23], 0
	v_mfma_f32_16x16x32_bf16 v[140:143], v[198:201], v[20:23], 0
	v_mfma_f32_16x16x32_bf16 v[136:139], v[202:205], v[20:23], 0
	v_mfma_f32_16x16x32_bf16 v[144:147], v[220:223], v[20:23], 0
	ds_read_b128 v[194:197], v168
	ds_read_b128 v[198:201], v168 offset:1024
	ds_read_b128 v[202:205], v168 offset:8192
	ds_read_b128 v[220:223], v168 offset:9216
	s_waitcnt lgkmcnt(8)
	v_mfma_f32_16x16x32_bf16 v[132:135], v[224:227], v[24:27], v[132:135]
	v_mfma_f32_16x16x32_bf16 v[140:143], v[228:231], v[24:27], v[140:143]
	v_mfma_f32_16x16x32_bf16 v[136:139], v[232:235], v[24:27], v[136:139]
	v_mfma_f32_16x16x32_bf16 v[144:147], v[4:7], v[24:27], v[144:147]
	s_waitcnt lgkmcnt(4)
	v_mfma_f32_16x16x32_bf16 v[132:135], v[8:11], v[28:31], v[132:135]
	v_mfma_f32_16x16x32_bf16 v[140:143], v[12:15], v[28:31], v[140:143]
	v_mfma_f32_16x16x32_bf16 v[136:139], v[16:19], v[28:31], v[136:139]
	v_mfma_f32_16x16x32_bf16 v[144:147], v[164:167], v[28:31], v[144:147]
	s_waitcnt lgkmcnt(0)
	v_mfma_f32_16x16x32_bf16 v[132:135], v[194:197], v[32:35], v[132:135]
	v_mfma_f32_16x16x32_bf16 v[140:143], v[198:201], v[32:35], v[140:143]
	v_mfma_f32_16x16x32_bf16 v[136:139], v[202:205], v[32:35], v[136:139]
	v_mfma_f32_16x16x32_bf16 v[144:147], v[220:223], v[32:35], v[144:147]
	s_cmp_ge_i32 s27, s40
	s_cbranch_scc1 .Lmoba_skipA
	s_add_i32 s32, s25, 64
	v_readfirstlane_b32 s98, v152
	v_readfirstlane_b32 s99, v153
	s_lshl_b32 s57, s32, 8
	s_add_u32 s98, s98, s57
	s_addc_u32 s99, s99, 0
	s_add_u32 m0, s79, 0x8000
	s_nop 0
	global_load_lds_dwordx4 v252, s[98:99]
	s_add_u32 m0, s79, 0x9000
	s_add_u32 s98, s98, 0x1000
	s_addc_u32 s99, s99, 0
	global_load_lds_dwordx4 v253, s[98:99]
	s_add_u32 m0, s79, 0xa000
	s_add_u32 s98, s98, 0x1000
	s_addc_u32 s99, s99, 0
	global_load_lds_dwordx4 v252, s[98:99]
	s_add_u32 m0, s79, 0xb000
	s_add_u32 s98, s98, 0x1000
	s_addc_u32 s99, s99, 0
	global_load_lds_dwordx4 v253, s[98:99]
	v_readfirstlane_b32 s98, v156
	v_readfirstlane_b32 s99, v157
	s_lshl_b32 s57, s32, 1
	s_add_u32 s98, s98, s57
	s_addc_u32 s99, s99, 0
	s_add_u32 m0, s79, 0xc000
	s_nop 0
	global_load_lds_dwordx4 v254, s[98:99]
	s_add_u32 m0, s79, 0xd000
	s_add_u32 s98, s98, 0x40000
	s_addc_u32 s99, s99, 0
	global_load_lds_dwordx4 v254, s[98:99]
	s_add_u32 m0, s79, 0xe000
	s_add_u32 s98, s98, 0x40000
	s_addc_u32 s99, s99, 0
	global_load_lds_dwordx4 v254, s[98:99]
	s_add_u32 m0, s79, 0xf000
	s_add_u32 s98, s98, 0x40000
	s_addc_u32 s99, s99, 0
	global_load_lds_dwordx4 v254, s[98:99]
	.Lmoba_skipA:
	s_nop 7
	s_cbranch_vccnz .LBB0_620
	v_cndmask_b32_e64 v4, v244, 0, s[6:7]
	s_mov_b32 s28, 0x3e0293ee
	v_pk_fma_f32 v[164:165], v[134:135], s[28:29], v[4:5] op_sel_hi:[1,0,0]
	v_pk_fma_f32 v[168:169], v[142:143], s[28:29], v[4:5] op_sel_hi:[1,0,0]
	v_pk_fma_f32 v[2:3], v[132:133], s[28:29], v[4:5] op_sel_hi:[1,0,0]
	v_max_f32_e32 v0, v164, v165
	v_pk_fma_f32 v[166:167], v[140:141], s[28:29], v[4:5] op_sel_hi:[1,0,0]
	v_max_f32_e32 v170, v168, v169
	v_max3_f32 v0, v2, v3, v0
	v_max3_f32 v170, v166, v167, v170
	s_mov_b32 s10, 0xff800000
	v_pk_fma_f32 v[172:173], v[138:139], s[28:29], v[4:5] op_sel_hi:[1,0,0]
	v_max3_f32 v0, v0, s10, v170
	v_pk_fma_f32 v[170:171], v[136:137], s[28:29], v[4:5] op_sel_hi:[1,0,0]
	v_max_f32_e32 v174, v172, v173
	v_pk_fma_f32 v[176:177], v[146:147], s[28:29], v[4:5] op_sel_hi:[1,0,0]
	v_max3_f32 v190, v170, v171, v174
	v_pk_fma_f32 v[174:175], v[144:145], s[28:29], v[4:5] op_sel_hi:[1,0,0]
	v_max_f32_e32 v191, v176, v177
	v_max3_f32 v191, v174, v175, v191
	v_max3_f32 v0, v0, v190, v191
	s_mov_b64 s[10:11], 0

; __device__ void moba_item(const P& p, int bh, int qt, char* smem) {
;     ...
;     if (tt + 2 < ntiles) {
;       const int k1 = (tt + 2) * 64;
; #pragma unroll
;       for (int i = 0; i < 4; ++i) {
;         rk[i] = *(const u32x4*)(Kp + (size_t)(k1 + kr + 16 * i) * 128 + kc * 8);
;         rv[i] = *(const u32x4*)(VT + (size_t)(vr + 32 * i) * 4096 + k1 + vc * 8);
;       }
;     }
;     const int blk = tt >> 2;
;     const bool own = (blk == qblk);
;     const bool rowvalid = own || ((mymask >> blk) & 1u);
;     if (__any(rowvalid)) {
;       const int key0 = tt * 64;
;       f32x4 sacc[2][2];
; #pragma unroll
;       for (int st = 0; st < 2; ++st)
; #pragma unroll
;         for (int kt = 0; kt < 2; ++kt) {
;           sacc[st][kt] = (f32x4){0.f, 0.f, 0.f, 0.f};
;           const int row = 32 * st + 8 * (li >> 2) + 4 * kt + (li & 3);
; #pragma unroll
;           for (int kk = 0; kk < 4; ++kk) {
;             const bf16x8 kf = *(const bf16x8*)(sK + row * 256 + (((kk * 4 + g) ^ li) << 4));
;             sacc[st][kt] = __builtin_amdgcn_mfma_f32_16x16x32_bf16(kf, qf[kk], sacc[st][kt], 0, 0, 0);
;           }
;         }
;       const bool diag = (tt == ntiles - 1);
;       float mx = -INFINITY;
;       if (diag || !__all(rowvalid)) {
; #pragma unroll
;         for (int st = 0; st < 2; ++st)
; #pragma unroll
;           for (int kt = 0; kt < 2; ++kt)
; #pragma unroll
;             for (int r = 0; r < 4; ++r) {
;               const int key = key0 + 32 * st + 8 * g + 4 * kt + r;
;               bool ok = rowvalid && (!diag || key <= qpos);
;               const float sv = ok ? sacc[st][kt][r] * SC : -INFINITY;
;               sacc[st][kt][r] = sv;
;               mx = fmaxf(mx, sv);
;             }
;       } else {
; #pragma unroll
;         for (int st = 0; st < 2; ++st)
; #pragma unroll
;           for (int kt = 0; kt < 2; ++kt) {
;             sacc[st][kt] *= SC;
;             mx = fmaxf(mx, fmaxf(fmaxf(sacc[st][kt][0], sacc[st][kt][1]), fmaxf(sacc[st][kt][2], sacc[st][kt][3])));
;           }
;       }
.LBB0_628:
	v_cndmask_b32_e64 v0, 0, 1, s[6:7]
	v_cmp_ne_u32_e32 vcc, 0, v0
	s_cbranch_vccz .Lmoba_lateB
	v_add_u32_e32 v2, v155, v151
	v_add_u32_e32 v3, v155, v178
	v_add_u32_e32 v168, v155, v179
	v_add_u32_e32 v169, v155, v180
	s_cmp_eq_u32 s24, s27
	s_cselect_b64 s[0:1], -1, 0
	s_and_b64 vcc, exec, s[0:1]
	s_mov_b64 s[10:11], s[0:1]
	ds_read_b128 v[194:197], v2 offset:32768
	ds_read_b128 v[198:201], v2 offset:33792
	ds_read_b128 v[202:205], v2 offset:40960
	ds_read_b128 v[220:223], v2 offset:41984
	ds_read_b128 v[224:227], v3 offset:32768
	ds_read_b128 v[228:231], v3 offset:33792
	ds_read_b128 v[232:235], v3 offset:40960
	ds_read_b128 v[4:7], v3 offset:41984
	ds_read_b128 v[8:11], v168 offset:32768
	ds_read_b128 v[12:15], v168 offset:33792
	ds_read_b128 v[16:19], v168 offset:40960
	ds_read_b128 v[164:167], v168 offset:41984
	s_waitcnt lgkmcnt(8)
	v_mfma_f32_16x16x32_bf16 v[132:135], v[194:197], v[20:23], 0
	v_mfma_f32_16x16x32_bf16 v[140:143], v[198:201], v[20:23], 0
	v_mfma_f32_16x16x32_bf16 v[136:139], v[202:205], v[20:23], 0
	v_mfma_f32_16x16x32_bf16 v[144:147], v[220:223], v[20:23], 0
	ds_read_b128 v[194:197], v169 offset:32768
	ds_read_b128 v[198:201], v169 offset:33792
	ds_read_b128 v[202:205], v169 offset:40960
	ds_read_b128 v[220:223], v169 offset:41984
	s_waitcnt lgkmcnt(8)
	v_mfma_f32_16x16x32_bf16 v[132:135], v[224:227], v[24:27], v[132:135]
	v_mfma_f32_16x16x32_bf16 v[140:143], v[228:231], v[24:27], v[140:143]
	v_mfma_f32_16x16x32_bf16 v[136:139], v[232:235], v[24:27], v[136:139]
	v_mfma_f32_16x16x32_bf16 v[144:147], v[4:7], v[24:27], v[144:147]
	s_waitcnt lgkmcnt(4)
	v_mfma_f32_16x16x32_bf16 v[132:135], v[8:11], v[28:31], v[132:135]
	v_mfma_f32_16x16x32_bf16 v[140:143], v[12:15], v[28:31], v[140:143]
	v_mfma_f32_16x16x32_bf16 v[136:139], v[16:19], v[28:31], v[136:139]
	v_mfma_f32_16x16x32_bf16 v[144:147], v[164:167], v[28:31], v[144:147]
	s_waitcnt lgkmcnt(0)
	v_mfma_f32_16x16x32_bf16 v[132:135], v[194:197], v[32:35], v[132:135]
	v_mfma_f32_16x16x32_bf16 v[140:143], v[198:201], v[32:35], v[140:143]
	v_mfma_f32_16x16x32_bf16 v[136:139], v[202:205], v[32:35], v[136:139]
	v_mfma_f32_16x16x32_bf16 v[144:147], v[220:223], v[32:35], v[144:147]
	s_cmp_lg_u32 s8, 0
	s_cbranch_scc1 .Lmoba_skipB
	s_add_i32 s32, s25, 128
	v_readfirstlane_b32 s98, v152
	v_readfirstlane_b32 s99, v153
	s_lshl_b32 s57, s32, 8
	s_add_u32 s98, s98, s57
	s_addc_u32 s99, s99, 0
	s_add_u32 m0, s79, 0x0
	s_nop 0
	global_load_lds_dwordx4 v252, s[98:99]
	s_add_u32 m0, s79, 0x1000
	s_add_u32 s98, s98, 0x1000
	s_addc_u32 s99, s99, 0
	global_load_lds_dwordx4 v253, s[98:99]
	s_add_u32 m0, s79, 0x2000
	s_add_u32 s98, s98, 0x1000
	s_addc_u32 s99, s99, 0
	global_load_lds_dwordx4 v252, s[98:99]
	s_add_u32 m0, s79, 0x3000
	s_add_u32 s98, s98, 0x1000
	s_addc_u32 s99, s99, 0
	global_load_lds_dwordx4 v253, s[98:99]
	v_readfirstlane_b32 s98, v156
	v_readfirstlane_b32 s99, v157
	s_lshl_b32 s57, s32, 1
	s_add_u32 s98, s98, s57
	s_addc_u32 s99, s99, 0
	s_add_u32 m0, s79, 0x4000
	s_nop 0
	global_load_lds_dwordx4 v254, s[98:99]
	s_add_u32 m0, s79, 0x5000
	s_add_u32 s98, s98, 0x40000
	s_addc_u32 s99, s99, 0
	global_load_lds_dwordx4 v254, s[98:99]
	s_add_u32 m0, s79, 0x6000
	s_add_u32 s98, s98, 0x40000
	s_addc_u32 s99, s99, 0
	global_load_lds_dwordx4 v254, s[98:99]
	s_add_u32 m0, s79, 0x7000
	s_add_u32 s98, s98, 0x40000
	s_addc_u32 s99, s99, 0
	global_load_lds_dwordx4 v254, s[98:99]
	.Lmoba_skipB:
	s_nop 7
	s_cbranch_vccnz .LBB0_632
	v_cndmask_b32_e64 v4, v244, 0, s[6:7]
	s_mov_b32 s28, 0x3e0293ee
	v_pk_fma_f32 v[164:165], v[134:135], s[28:29], v[4:5] op_sel_hi:[1,0,0]
	v_pk_fma_f32 v[2:3], v[132:133], s[28:29], v[4:5] op_sel_hi:[1,0,0]
	v_max_f32_e32 v166, v164, v165
	v_pk_fma_f32 v[168:169], v[142:143], s[28:29], v[4:5] op_sel_hi:[1,0,0]
	v_max3_f32 v170, v2, v3, v166
	v_pk_fma_f32 v[166:167], v[140:141], s[28:29], v[4:5] op_sel_hi:[1,0,0]
	v_max_f32_e32 v171, v168, v169
	v_max3_f32 v171, v166, v167, v171
	s_mov_b32 s10, 0xff800000
	v_pk_fma_f32 v[172:173], v[138:139], s[28:29], v[4:5] op_sel_hi:[1,0,0]
	v_max3_f32 v189, v170, s10, v171
	v_pk_fma_f32 v[170:171], v[136:137], s[28:29], v[4:5] op_sel_hi:[1,0,0]
	v_max_f32_e32 v174, v172, v173
	v_pk_fma_f32 v[176:177], v[146:147], s[28:29], v[4:5] op_sel_hi:[1,0,0]
	v_max3_f32 v191, v170, v171, v174
	v_pk_fma_f32 v[174:175], v[144:145], s[28:29], v[4:5] op_sel_hi:[1,0,0]
	v_max_f32_e32 v192, v176, v177
	v_max3_f32 v192, v174, v175, v192
	v_max3_f32 v189, v189, v191, v192
	s_mov_b64 s[10:11], 0
